# G3->Q0 and WO->Q1 seams XCD-local (leader releases its XCD without write-back / top-level round) when a run-time census confirms blockIdx%8 == XCD
# speedup vs baseline: 1.0075x; 1.0075x over previous
_Z4mega4Args:
	s_load_dwordx8 s[52:59], s[0:1], 0x60
	s_load_dwordx8 s[60:67], s[0:1], 0x40
	s_load_dword s87, s[0:1], 0x80
	s_add_u32 s20, s0, 0x78
	v_and_b32_e32 v197, 0x3ff, v0
	s_addc_u32 s21, s1, 0
	v_readfirstlane_b32 s3, v197
	v_cmp_gt_u32_e32 vcc, 16, v197
	s_nop 0
	v_writelane_b32 v248, s3, 0
	v_writelane_b32 v248, 0, 20
	s_and_saveexec_b64 s[4:5], vcc
	v_lshl_add_u32 v1, v197, 2, 0
	v_add_u32_e32 v1, 0x20000, v1
	v_mov_b32_e32 v2, 0
	ds_write_b32 v1, v2
	s_or_b64 exec, exec, s[4:5]
	s_load_dwordx16 s[36:51], s[0:1], 0x0
	s_waitcnt lgkmcnt(0)
	s_barrier
	s_add_u32 s88, s54, 0x4000
	s_getreg_b32 s0, hwreg(HW_REG_XCC_ID, 0, 4)
	s_addc_u32 s89, s55, 0
	s_and_b32 s93, s0, 15
	v_cmp_eq_u32_e64 s[0:1], 0, v197
	s_mov_b64 s[4:5], exec
	s_nop 0
	v_writelane_b32 v248, s0, 1
	s_nop 1
	v_writelane_b32 v248, s1, 2
	s_and_b64 s[0:1], s[4:5], s[0:1]
	s_mov_b64 exec, s[0:1]
	s_cbranch_execz .LBB0_5
	s_mov_b64 s[6:7], exec
	v_mbcnt_lo_u32_b32 v1, s6, 0
	v_mbcnt_hi_u32_b32 v1, s7, v1
	v_cmp_eq_u32_e32 vcc, 0, v1
	s_and_b64 s[0:1], exec, vcc
	s_mov_b64 exec, s[0:1]
	s_cbranch_execz .LBB0_5
	s_lshl_b32 s0, s93, 8
	s_bcnt1_i32_b64 s1, s[6:7]
	v_mov_b32_e32 v1, s0
	v_mov_b32_e32 v2, s1
	global_atomic_add v1, v2, s[88:89] offset:1024

.LBB0_137:
	s_cmp_gt_i32 s57, 1
	s_cselect_b64 s[4:5], -1, 0
	s_and_b64 s[0:1], s[22:23], s[4:5]
	s_andn2_b64 vcc, exec, s[0:1]
	s_cbranch_vccnz .LBB0_149
	s_waitcnt vmcnt(0)
	s_waitcnt vmcnt(0) lgkmcnt(0)
	s_barrier
	s_mov_b64 s[6:7], exec
	v_readlane_b32 s0, v248, 1
	v_readlane_b32 s1, v248, 2
	s_and_b64 s[0:1], s[6:7], s[0:1]
	s_mov_b64 exec, s[0:1]
	s_cbranch_execz .Lxb0_228
	s_add_u32 s0, s54, 0x10000
	s_addc_u32 s1, s55, 0
	s_and_b32 s8, s2, 7
	s_lshl_b32 s8, s8, 2
	v_mov_b32_e32 v0, s8
	s_lshl_b32 s8, 1, s93
	v_mov_b32_e32 v2, s8
	global_atomic_or v0, v2, s[0:1]
	s_add_i32 s0, 0, 0x20020
	v_mov_b32_e32 v0, s0
	s_waitcnt vmcnt(0) expcnt(0) lgkmcnt(0)
	ds_read_b32 v2, v0
	s_add_i32 s0, 0, 0x20024
	v_mov_b32_e32 v0, s0
	ds_read_b32 v0, v0
	s_waitcnt lgkmcnt(1)
	v_cmp_ne_u32_e32 vcc, 0, v2
	s_cbranch_vccnz .Lxb0_192
	s_add_u32 s8, s54, 0x4200
	s_addc_u32 s9, s55, 0
	s_add_u32 s10, s54, 0x4400
	s_addc_u32 s11, s55, 0
	s_add_u32 s12, s54, 0x4500
	s_addc_u32 s13, s55, 0
	s_add_u32 s14, s54, 0x4600
	s_addc_u32 s15, s55, 0
	s_add_u32 s16, s54, 0x4700
	s_addc_u32 s17, s55, 0
	s_add_u32 s20, s54, 0x4800
	s_addc_u32 s21, s55, 0
	s_add_u32 s22, s54, 0x4900
	s_addc_u32 s23, s55, 0
	s_add_u32 s24, s54, 0x4a00
	s_addc_u32 s25, s55, 0
	s_add_u32 s26, s54, 0x4b00
	s_addc_u32 s27, s55, 0
	s_add_u32 s28, s54, 0x4c00
	s_addc_u32 s29, s55, 0
	s_add_u32 s30, s54, 0x4d00
	s_addc_u32 s31, s55, 0
	s_add_u32 s34, s54, 0x4e00
	s_addc_u32 s35, s55, 0
	s_add_u32 s42, s54, 0x4f00
	s_addc_u32 s43, s55, 0
	s_add_u32 s44, s54, 0x5000
	s_addc_u32 s45, s55, 0
	s_add_u32 s46, s54, 0x5100
	s_addc_u32 s47, s55, 0
	s_add_u32 s50, s54, 0x5200
	s_addc_u32 s51, s55, 0
	s_mul_i32 s0, s59, s87
	s_add_u32 s60, s54, 0x5300
	s_mul_i32 s0, s0, s58
	s_addc_u32 s61, s55, 0
	s_mov_b32 s1, 1
	v_mov_b32_e32 v16, 0
	s_branch .Lxb0_180

.Lxb0_228:
	s_or_b64 exec, exec, s[6:7]
	s_add_u32 s0, s54, 0x10000
	s_addc_u32 s1, s55, 0
	v_mov_b32_e32 v0, 0
	global_load_dwordx4 v[4:7], v0, s[0:1] sc1
	global_load_dwordx4 v[8:11], v0, s[0:1] offset:16 sc1
	v_mov_b32_e32 v14, 0
	s_waitcnt vmcnt(0)
	v_or3_b32 v12, v4, v5, v6
	v_or3_b32 v13, v7, v8, v9
	v_or3_b32 v12, v12, v10, v11
	v_or_b32_e32 v12, v12, v13
	v_bcnt_u32_b32 v12, v12, 0
	v_xor_b32_e32 v12, 8, v12
	v_add_u32_e32 v13, -1, v4
	v_and_b32_e32 v13, v13, v4
	v_or_b32_e32 v14, v14, v13
	v_add_u32_e32 v13, -1, v5
	v_and_b32_e32 v13, v13, v5
	v_or_b32_e32 v14, v14, v13
	v_add_u32_e32 v13, -1, v6
	v_and_b32_e32 v13, v13, v6
	v_or_b32_e32 v14, v14, v13
	v_add_u32_e32 v13, -1, v7
	v_and_b32_e32 v13, v13, v7
	v_or_b32_e32 v14, v14, v13
	v_add_u32_e32 v13, -1, v8
	v_and_b32_e32 v13, v13, v8
	v_or_b32_e32 v14, v14, v13
	v_add_u32_e32 v13, -1, v9
	v_and_b32_e32 v13, v13, v9
	v_or_b32_e32 v14, v14, v13
	v_add_u32_e32 v13, -1, v10
	v_and_b32_e32 v13, v13, v10
	v_or_b32_e32 v14, v14, v13
	v_add_u32_e32 v13, -1, v11
	v_and_b32_e32 v13, v13, v11
	v_or_b32_e32 v14, v14, v13
	v_or_b32_e32 v14, v14, v12
	s_nop 1
	v_readfirstlane_b32 s0, v14
	s_cmp_eq_u32 s0, 0
	s_cselect_b32 s0, 1, 0
	s_nop 3
	v_writelane_b32 v248, s0, 20
	s_waitcnt lgkmcnt(0)
	s_barrier

.LBB0_441:
	s_andn2_saveexec_b64 s[0:1], s[10:11]
	s_cbranch_execz .LBB0_461
	s_mov_b64 s[10:11], exec
	v_readlane_b32 s0, v248, 20
	s_cmp_eq_u32 s0, 1
	s_cbranch_scc0 .Lglob_4
	buffer_inv sc1
	s_branch .Lloc_4
.Lglob_4:
	buffer_wbl2 sc1
	s_waitcnt lgkmcnt(0)
	s_waitcnt vmcnt(0)
	buffer_inv sc1
	v_mbcnt_lo_u32_b32 v1, s10, 0
	v_mbcnt_hi_u32_b32 v1, s11, v1
	v_cmp_eq_u32_e32 vcc, 0, v1
	s_and_saveexec_b64 s[12:13], vcc
	s_cbranch_execz .LBB0_444
	s_bcnt1_i32_b64 s0, s[10:11]
	v_mov_b32_e32 v2, 0x7000
	v_mov_b32_e32 v3, s0
	global_atomic_add v2, v2, v3, s[54:55] offset:1024 sc0

.Lloc_4:
	s_mov_b64 s[10:11], exec
	v_mbcnt_lo_u32_b32 v0, s10, 0
	v_mbcnt_hi_u32_b32 v0, s11, v0
	v_cmp_eq_u32_e32 vcc, 0, v0
	s_waitcnt vmcnt(0)
	s_and_saveexec_b64 s[12:13], vcc
	s_cbranch_execz .LBB0_460
	s_bcnt1_i32_b64 s0, s[10:11]
	v_mov_b32_e32 v0, 0x2000
	v_mov_b32_e32 v1, s0
	global_atomic_add v0, v1, s[8:9] offset:1024
